# grid barrier: non-leader workgroups poll the cross-XCD generation word directly (one hop less)
# speedup vs baseline: 1.0170x; 1.0072x over previous
.LBB0_1206:
	v_readlane_b32 s2, v254, 3
	v_readlane_b32 s3, v254, 4
	v_cvt_f32_u32_e32 v1, v2
	v_sub_u32_e32 v4, 0, v2
	v_rcp_iflag_f32_e32 v1, v1
	s_nop 1
	global_atomic_add v3, v33, v179, s[2:3] sc0
	v_mul_f32_e32 v1, 0x4f7ffffe, v1
	v_cvt_u32_f32_e32 v1, v1
	v_mul_lo_u32 v4, v4, v1
	v_mul_hi_u32 v4, v1, v4
	v_add_u32_e32 v1, v1, v4
	s_waitcnt vmcnt(0)
	v_mul_hi_u32 v1, v3, v1
	v_mul_lo_u32 v4, v1, v2
	v_sub_u32_e32 v4, v3, v4
	v_add_u32_e32 v5, 1, v1
	v_cmp_ge_u32_e32 vcc, v4, v2
	v_add_u32_e32 v3, 1, v3
	s_nop 0
	v_cndmask_b32_e32 v1, v1, v5, vcc
	v_sub_u32_e32 v5, v4, v2
	v_cndmask_b32_e32 v4, v4, v5, vcc
	v_add_u32_e32 v5, 1, v1
	v_cmp_ge_u32_e32 vcc, v4, v2
	s_nop 1
	v_cndmask_b32_e32 v1, v1, v5, vcc
	v_mul_lo_u32 v4, v2, v1
	v_add_u32_e32 v2, v4, v2
	v_cmp_ne_u32_e32 vcc, v3, v2
	s_and_saveexec_b64 s[2:3], vcc
	s_xor_b64 s[26:27], exec, s[2:3]
	s_cbranch_execz .LBB0_1220
	v_readlane_b32 s2, v254, 9
	v_readlane_b32 s3, v254, 10
	s_waitcnt lgkmcnt(0)
	s_nop 3
	buffer_inv sc1
	global_load_dword v0, v33, s[2:3] sc1
	s_waitcnt vmcnt(0)
	v_cmp_eq_u32_e32 vcc, v0, v1
	s_and_saveexec_b64 s[34:35], vcc
	s_cbranch_execz .LBB0_1219
	s_mov_b32 s0, 1
	s_mov_b64 s[38:39], 0
	s_branch .LBB0_1210

.LBB0_1214:
	v_readlane_b32 s2, v254, 9
	v_readlane_b32 s3, v254, 10
	s_add_i32 s0, s0, 1
	s_mov_b64 s[46:47], -1
	s_nop 2
	global_load_dword v0, v33, s[2:3] sc1
	s_waitcnt vmcnt(0)
	v_cmp_ne_u32_e32 vcc, v0, v1
	s_orn2_b64 s[44:45], vcc, exec
	s_branch .LBB0_1209
